# spatial gating unit: w_s and GVT tiles staged through LDS with coalesced loads + hoisted gain loads; sc1 stores P5 P9
# speedup vs baseline: 1.0190x; 1.0048x over previous
.LBB0_969:
	s_or_b64 exec, exec, s[14:15]
	s_lshl_b32 s10, s21, 7
	v_add_u32_e32 v168, s10, v136
	v_or_b32_e32 v146, s12, v198
	v_ashrrev_i32_e32 v147, 31, v146
	v_lshlrev_b64 v[148:149], 10, v[146:147]
	v_or_b32_e32 v132, s10, v198
	v_lshl_add_u64 v[148:149], s[2:3], 0, v[148:149]
	s_lshl_b32 s10, s21, 8
	v_lshl_add_u64 v[148:149], v[148:149], 0, s[10:11]
	v_readlane_b32 s36, v253, 21
	v_lshl_add_u64 v[148:149], v[148:149], 0, v[140:141]
	v_lshlrev_b32_e32 v132, 2, v132
	v_readlane_b32 s37, v253, 22
	v_lshl_add_u64 v[148:149], v[148:149], 0, v[142:143]
	v_readlane_b32 s38, v253, 23
	v_readlane_b32 s39, v253, 24
	v_readlane_b32 s40, v253, 25
	v_readlane_b32 s41, v253, 26
	global_load_dword v145, v132, s[36:37]
	global_load_dwordx2 v[162:163], v[148:149], off nt
	global_load_dwordx2 v[160:161], v[148:149], off offset:16 nt
	global_load_dwordx2 v[158:159], v[148:149], off offset:32 nt
	global_load_dwordx2 v[156:157], v[148:149], off offset:48 nt
	global_load_dwordx2 v[154:155], v[148:149], off offset:64 nt
	global_load_dwordx2 v[152:153], v[148:149], off offset:80 nt
	global_load_dwordx2 v[150:151], v[148:149], off offset:96 nt
	s_nop 0
	global_load_dwordx2 v[148:149], v[148:149], off offset:112 nt
	s_waitcnt lgkmcnt(0)
	s_add_u32 s76, s74, 0x4b00000
	s_addc_u32 s77, s75, 0
	v_lshrrev_b32_e32 v0, 6, v215
	v_lshrrev_b32_e32 v1, 5, v214
	v_and_b32_e32 v2, 31, v214
	v_lshlrev_b32_e32 v2, 4, v2
	v_lshl_add_u32 v3, v0, 4, v1
	v_lshl_add_u32 v4, v3, 9, v2
	s_lshl_b32 s10, s21, 16
	v_add_u32_e32 v4, s10, v4
	v_add_u32_e32 v5, 0x1000, v4
	global_load_dwordx4 v[216:219], v4, s[26:27]
	global_load_dwordx4 v[220:223], v4, s[26:27] offset:1024
	global_load_dwordx4 v[224:227], v4, s[26:27] offset:2048
	global_load_dwordx4 v[228:231], v4, s[26:27] offset:3072
	global_load_dwordx4 v[232:235], v5, s[26:27]
	global_load_dwordx4 v[236:239], v5, s[26:27] offset:1024
	global_load_dwordx4 v[240:243], v5, s[26:27] offset:2048
	global_load_dwordx4 v[244:247], v5, s[26:27] offset:3072
	v_mul_u32_u24_e32 v6, 0x210, v3
	v_add_u32_e32 v6, 0x9000, v6
	v_add_u32_e32 v6, v6, v2
	v_lshrrev_b32_e32 v7, 4, v214
	v_and_b32_e32 v8, 15, v214
	v_lshlrev_b32_e32 v8, 4, v8
	v_lshl_add_u32 v9, v0, 4, v7
	v_mul_u32_u24_e32 v10, 0x110, v9
	v_add_u32_e32 v10, 0x400, v10
	v_add_u32_e32 v10, v10, v8
	s_lshl_b32 s10, s21, 7
	v_add_u32_e32 v9, s10, v9
	v_lshlrev_b32_e32 v9, 14, v9
	s_lshl_b32 s10, s12, 1
	v_add3_u32 v9, v9, v8, s10
	v_add_u32_e32 v11, 0x10000, v9
	global_load_dwordx4 v[178:181], v9, s[76:77]
	global_load_dwordx4 v[182:185], v11, s[76:77]
	v_add_u32_e32 v9, 0x20000, v9
	v_add_u32_e32 v11, 0x20000, v11
	global_load_dwordx4 v[186:189], v9, s[76:77]
	global_load_dwordx4 v[190:193], v11, s[76:77]
	v_readlane_b32 s42, v253, 27
	v_readlane_b32 s43, v253, 28
	v_readlane_b32 s44, v253, 29
	v_readlane_b32 s45, v253, 30
	v_readlane_b32 s46, v253, 31
	v_readlane_b32 s47, v253, 32
	v_readlane_b32 s48, v253, 33
	v_readlane_b32 s49, v253, 34
	v_readlane_b32 s50, v253, 35
	v_readlane_b32 s51, v253, 36
	s_and_saveexec_b64 s[12:13], s[4:5]
	s_cbranch_execz .LBB0_971
	s_waitcnt vmcnt(0)
	v_mov_b32_e32 v170, v17
	v_mov_b32_e32 v171, v18
	v_mov_b32_e32 v17, v19
	v_pk_add_f32 v[16:17], v[170:171], v[16:17]
	s_nop 0
	v_add_f32_e32 v16, v16, v17
	v_fmamk_f32 v16, v16, 0x3c000000, v166
	v_rsq_f32_e32 v16, v16
	ds_write_b32 v137, v16
.LBB0_971:
	s_or_b64 exec, exec, s[12:13]
	s_waitcnt vmcnt(0)
	ds_write_b128 v6, v[216:219]
	ds_write_b128 v6, v[220:223] offset:1056
	ds_write_b128 v6, v[224:227] offset:2112
	ds_write_b128 v6, v[228:231] offset:3168
	ds_write_b128 v6, v[232:235] offset:4224
	ds_write_b128 v6, v[236:239] offset:5280
	ds_write_b128 v6, v[240:243] offset:6336
	ds_write_b128 v6, v[244:247] offset:7392
	ds_write_b128 v10, v[178:181]
	ds_write_b128 v10, v[182:185] offset:1088
	ds_write_b128 v10, v[186:189] offset:2176
	ds_write_b128 v10, v[190:193] offset:3264
	s_waitcnt lgkmcnt(0)
	s_barrier
	v_mul_u32_u24_e32 v252, 0x210, v198
	v_add_u32_e32 v252, v252, v164
	v_add_u32_e32 v252, 0x9000, v252
	v_add_u32_e32 v169, v136, v196
	v_mul_u32_u24_e32 v169, 0x110, v169
	v_lshl_add_u32 v169, v197, 2, v169
	v_add_u32_e32 v169, 0x400, v169
	ds_read_b128 v[128:131], v252
	ds_read_b128 v[124:127], v252 offset:16
	ds_read_b128 v[24:27], v252 offset:64
	ds_read_b128 v[20:23], v252 offset:80
	ds_read_b128 v[120:123], v252 offset:128
	ds_read_b128 v[116:119], v252 offset:144
	ds_read_b128 v[112:115], v252 offset:192
	ds_read_b128 v[104:107], v252 offset:208
	ds_read_b128 v[96:99], v252 offset:256
	ds_read_b128 v[92:95], v252 offset:272
	ds_read_b128 v[88:91], v252 offset:320
	ds_read_b128 v[80:83], v252 offset:336
	s_waitcnt lgkmcnt(0)
	ds_read_b128 v[72:75], v252 offset:384
	ds_read_b128 v[68:71], v252 offset:400
	ds_read_b128 v[64:67], v252 offset:448
	ds_read_b128 v[56:59], v252 offset:464
	ds_read_b128 v[12:15], v169
	ds_read_b128 v[108:111], v169 offset:32
	ds_read_b128 v[100:103], v169 offset:64
	ds_read_b128 v[84:87], v169 offset:96
	ds_read_b128 v[76:79], v169 offset:128
	ds_read_b128 v[60:63], v169 offset:160
	ds_read_b128 v[8:11], v169 offset:192
	ds_read_b128 v[4:7], v169 offset:224
	s_waitcnt lgkmcnt(0)
	ds_read_b128 v[0:3], v169 offset:8704
	ds_read_b128 v[52:55], v169 offset:8736
	ds_read_b128 v[48:51], v169 offset:8768
	ds_read_b128 v[44:47], v169 offset:8800
	ds_read_b128 v[40:43], v169 offset:8832
	ds_read_b128 v[36:39], v169 offset:8864
	ds_read_b128 v[32:35], v169 offset:8896
	ds_read_b128 v[28:31], v169 offset:8928
	v_or_b32_e32 v252, v168, v197
	v_lshlrev_b32_e32 v252, 2, v252
	global_load_dwordx4 v[216:219], v252, s[24:25]
	global_load_dwordx4 v[220:223], v252, s[24:25] offset:32
	global_load_dwordx4 v[224:227], v252, s[24:25] offset:64
	global_load_dwordx4 v[228:231], v252, s[24:25] offset:96
	global_load_dwordx4 v[232:235], v252, s[24:25] offset:128
	global_load_dwordx4 v[236:239], v252, s[24:25] offset:160
	global_load_dwordx4 v[240:243], v252, s[24:25] offset:192
	global_load_dwordx4 v[244:247], v252, s[24:25] offset:224
	global_load_dwordx4 v[178:181], v252, s[40:41]
	global_load_dwordx4 v[182:185], v252, s[40:41] offset:32
	global_load_dwordx4 v[186:189], v252, s[40:41] offset:64
	global_load_dwordx4 v[190:193], v252, s[40:41] offset:96
	global_load_dwordx4 v[200:203], v252, s[40:41] offset:128
	global_load_dwordx4 v[204:207], v252, s[40:41] offset:160
	global_load_dwordx4 v[208:211], v252, s[40:41] offset:192
	global_load_dwordx4 v[248:251], v252, s[40:41] offset:224
	s_waitcnt lgkmcnt(0)
	ds_read_b128 v[16:19], v164
	ds_read_b128 v[170:173], v164 offset:16
	v_readlane_b32 s36, v253, 5
	v_readlane_b32 s44, v253, 13
	v_readlane_b32 s45, v253, 14
	s_waitcnt lgkmcnt(1)
	v_mul_f32_e32 v16, v128, v16
	s_waitcnt lgkmcnt(0)
	v_mul_f32_e32 v128, v124, v170
	v_mul_f32_e32 v17, v129, v17
	v_mul_f32_e32 v129, v125, v171
	v_mul_f32_e32 v18, v130, v18
	v_mul_f32_e32 v130, v126, v172
	v_mul_f32_e32 v19, v131, v19
	v_mul_f32_e32 v127, v127, v173
	v_cvt_pk_bf16_f32 v124, v16, v17
	v_cvt_pk_bf16_f32 v125, v18, v19
	v_cvt_pk_bf16_f32 v126, v128, v129
	v_cvt_pk_bf16_f32 v127, v130, v127
	ds_read_b128 v[16:19], v164 offset:64
	ds_read_b128 v[128:131], v164 offset:80
	v_readlane_b32 s46, v253, 15
	v_readlane_b32 s47, v253, 16
	v_readlane_b32 s48, v253, 17
	s_waitcnt lgkmcnt(1)
	v_mul_f32_e32 v16, v24, v16
	s_waitcnt lgkmcnt(0)
	v_mul_f32_e32 v20, v20, v128
	v_mul_f32_e32 v17, v25, v17
	v_mul_f32_e32 v21, v21, v129
	v_mul_f32_e32 v18, v26, v18
	v_mul_f32_e32 v22, v22, v130
	v_mul_f32_e32 v19, v27, v19
	v_mul_f32_e32 v23, v23, v131
	v_cvt_pk_bf16_f32 v128, v16, v17
	v_cvt_pk_bf16_f32 v129, v18, v19
	v_cvt_pk_bf16_f32 v130, v20, v21
	v_cvt_pk_bf16_f32 v131, v22, v23
	v_mfma_f32_32x32x16_bf16 v[12:27], v[12:15], v[124:127], 0
	ds_read_b128 v[170:173], v164 offset:128
	ds_read_b128 v[174:177], v164 offset:144
	v_readlane_b32 s49, v253, 18
	s_mov_b64 s[24:25], s[44:45]
	s_mov_b64 s[28:29], s[48:49]
	s_waitcnt lgkmcnt(1)
	v_mul_f32_e32 v120, v120, v170
	s_waitcnt lgkmcnt(0)
	v_mul_f32_e32 v132, v116, v174
	v_mul_f32_e32 v116, v121, v171
	v_mfma_f32_32x32x16_bf16 v[12:27], v[108:111], v[128:131], v[12:27]
	v_mul_f32_e32 v121, v117, v175
	v_mul_f32_e32 v117, v122, v172
	v_mul_f32_e32 v122, v118, v176
	v_mul_f32_e32 v118, v123, v173
	v_mul_f32_e32 v119, v119, v177
	v_cvt_pk_bf16_f32 v116, v120, v116
	v_cvt_pk_bf16_f32 v117, v117, v118
	v_cvt_pk_bf16_f32 v118, v132, v121
	v_cvt_pk_bf16_f32 v119, v122, v119
	ds_read_b128 v[120:123], v164 offset:192
	ds_read_b128 v[170:173], v164 offset:208
	v_mfma_f32_32x32x16_bf16 v[12:27], v[100:103], v[116:119], v[12:27]
	v_readlane_b32 s37, v253, 6
	v_readlane_b32 s38, v253, 7
	s_waitcnt lgkmcnt(1)
	v_mul_f32_e32 v108, v112, v120
	s_waitcnt lgkmcnt(0)
	v_mul_f32_e32 v109, v104, v170
	v_mul_f32_e32 v104, v113, v121
	v_mul_f32_e32 v110, v105, v171
	v_mul_f32_e32 v105, v114, v122
	v_mul_f32_e32 v111, v106, v172
	v_mul_f32_e32 v106, v115, v123
	v_mul_f32_e32 v107, v107, v173
	v_cvt_pk_bf16_f32 v104, v108, v104
	v_cvt_pk_bf16_f32 v105, v105, v106
	v_cvt_pk_bf16_f32 v106, v109, v110
	v_cvt_pk_bf16_f32 v107, v111, v107
	ds_read_b128 v[108:111], v164 offset:256
	ds_read_b128 v[112:115], v164 offset:272
	v_mfma_f32_32x32x16_bf16 v[12:27], v[84:87], v[104:107], v[12:27]
	v_readlane_b32 s39, v253, 8
	v_readlane_b32 s40, v253, 9
	s_waitcnt lgkmcnt(1)
	v_mul_f32_e32 v96, v96, v108
	s_waitcnt lgkmcnt(0)
	v_mul_f32_e32 v100, v92, v112
	v_mul_f32_e32 v92, v97, v109
	v_mul_f32_e32 v97, v93, v113
	v_mul_f32_e32 v93, v98, v110
	v_mul_f32_e32 v98, v94, v114
	v_mul_f32_e32 v94, v99, v111
	v_mul_f32_e32 v95, v95, v115
	v_cvt_pk_bf16_f32 v92, v96, v92
	v_cvt_pk_bf16_f32 v93, v93, v94
	v_cvt_pk_bf16_f32 v94, v100, v97
	v_cvt_pk_bf16_f32 v95, v98, v95
	ds_read_b128 v[96:99], v164 offset:320
	ds_read_b128 v[100:103], v164 offset:336
	v_mfma_f32_32x32x16_bf16 v[12:27], v[76:79], v[92:95], v[12:27]
	v_readlane_b32 s41, v253, 10
	v_readlane_b32 s42, v253, 11
	s_waitcnt lgkmcnt(1)
	v_mul_f32_e32 v84, v88, v96
	s_waitcnt lgkmcnt(0)
	v_mul_f32_e32 v85, v80, v100
	v_mul_f32_e32 v80, v89, v97
	v_mul_f32_e32 v86, v81, v101
	v_mul_f32_e32 v81, v90, v98
	v_mul_f32_e32 v87, v82, v102
	v_mul_f32_e32 v82, v91, v99
	v_mul_f32_e32 v83, v83, v103
	v_cvt_pk_bf16_f32 v80, v84, v80
	v_cvt_pk_bf16_f32 v81, v81, v82
	v_cvt_pk_bf16_f32 v82, v85, v86
	v_cvt_pk_bf16_f32 v83, v87, v83
	ds_read_b128 v[84:87], v164 offset:384
	ds_read_b128 v[88:91], v164 offset:400
	v_mfma_f32_32x32x16_bf16 v[12:27], v[60:63], v[80:83], v[12:27]
	v_readlane_b32 s43, v253, 12
	v_readlane_b32 s50, v253, 19
	s_waitcnt lgkmcnt(1)
	v_mul_f32_e32 v72, v72, v84
	s_waitcnt lgkmcnt(0)
	v_mul_f32_e32 v76, v68, v88
	v_mul_f32_e32 v68, v73, v85
	v_mul_f32_e32 v73, v69, v89
	v_mul_f32_e32 v69, v74, v86
	v_mul_f32_e32 v74, v70, v90
	v_mul_f32_e32 v70, v75, v87
	v_mul_f32_e32 v71, v71, v91
	v_cvt_pk_bf16_f32 v68, v72, v68
	v_cvt_pk_bf16_f32 v69, v69, v70
	v_cvt_pk_bf16_f32 v70, v76, v73
	v_cvt_pk_bf16_f32 v71, v74, v71
	ds_read_b128 v[72:75], v164 offset:448
	ds_read_b128 v[76:79], v164 offset:464
	v_readlane_b32 s51, v253, 20
	s_mov_b64 s[26:27], s[46:47]
	v_readlane_b32 s36, v253, 21
	s_waitcnt lgkmcnt(1)
	v_mul_f32_e32 v60, v64, v72
	s_waitcnt lgkmcnt(0)
	v_mul_f32_e32 v56, v56, v76
	v_mul_f32_e32 v61, v65, v73
	v_mul_f32_e32 v57, v57, v77
	v_mul_f32_e32 v62, v66, v74
	v_mul_f32_e32 v63, v58, v78
	v_mul_f32_e32 v64, v67, v75
	v_mul_f32_e32 v65, v59, v79
	v_cvt_pk_bf16_f32 v58, v60, v61
	v_cvt_pk_bf16_f32 v59, v62, v64
	v_cvt_pk_bf16_f32 v60, v56, v57
	v_or_b32_e32 v56, v168, v197
	v_lshlrev_b32_e32 v66, 2, v56
	v_cvt_pk_bf16_f32 v61, v63, v65
	v_readlane_b32 s40, v253, 25
	v_readlane_b32 s41, v253, 26
	v_mfma_f32_32x32x16_bf16 v[12:27], v[8:11], v[68:71], v[12:27]
	v_lshlrev_b32_e32 v132, 1, v56
	v_lshlrev_b32_e32 v79, 16, v160
	v_and_b32_e32 v84, 0xffff0000, v160
	v_lshlrev_b32_e32 v85, 16, v161
	v_and_b32_e32 v86, 0xffff0000, v161
	v_readlane_b32 s37, v253, 22
	v_mfma_f32_32x32x16_bf16 v[12:27], v[4:7], v[58:61], v[12:27]
	v_lshlrev_b32_e32 v6, 16, v162
	v_lshlrev_b64 v[4:5], 11, v[146:147]
	v_lshl_add_u64 v[4:5], s[8:9], 0, v[4:5]
	v_lshl_add_u64 v[56:57], v[4:5], 0, v[132:133]
	v_readlane_b32 s38, v253, 23
	v_readlane_b32 s39, v253, 24
	v_readlane_b32 s42, v253, 27
	v_readlane_b32 s43, v253, 28
	v_readlane_b32 s44, v253, 29
	v_readlane_b32 s45, v253, 30
	v_readlane_b32 s46, v253, 31
	v_readlane_b32 s47, v253, 32
	v_readlane_b32 s48, v253, 33
	v_readlane_b32 s49, v253, 34
	v_readlane_b32 s50, v253, 35
	v_readlane_b32 s51, v253, 36
	s_waitcnt vmcnt(0)
	v_fma_f32 v7, v12, v216, v145
	v_mul_f32_e32 v67, v7, v6
	v_and_b32_e32 v6, 0xffff0000, v162
	v_fma_f32 v7, v13, v217, v145
	v_mul_f32_e32 v76, v7, v6
	v_lshlrev_b32_e32 v6, 16, v163
	v_fma_f32 v7, v14, v218, v145
	v_mul_f32_e32 v77, v7, v6
	v_and_b32_e32 v6, 0xffff0000, v163
	v_fma_f32 v7, v15, v219, v145
	v_mul_f32_e32 v78, v7, v6
	v_mul_f32_e32 v6, v178, v67
	v_mul_f32_e32 v7, v179, v76
	v_cvt_pk_bf16_f32 v6, v6, v7
	v_mul_f32_e32 v7, v180, v77
	v_mul_f32_e32 v8, v181, v78
	v_cvt_pk_bf16_f32 v7, v7, v8
	global_store_dwordx2 v[56:57], v[6:7], off offset:1024
	v_mfma_f32_32x32x16_bf16 v[0:15], v[0:3], v[124:127], 0
	v_fma_f32 v16, v16, v220, v145
	v_mfma_f32_32x32x16_bf16 v[0:15], v[52:55], v[128:131], v[0:15]
	v_fma_f32 v17, v17, v221, v145
	v_fma_f32 v18, v18, v222, v145
	v_fma_f32 v19, v19, v223, v145
	v_mul_f32_e32 v52, v16, v79
	v_mul_f32_e32 v53, v17, v84
	v_mul_f32_e32 v54, v18, v85
	v_mul_f32_e32 v55, v19, v86
	v_mul_f32_e32 v16, v182, v52
	v_mul_f32_e32 v17, v183, v53
	v_mul_f32_e32 v18, v184, v54
	v_mul_f32_e32 v19, v185, v55
	v_cvt_pk_bf16_f32 v16, v16, v17
	v_cvt_pk_bf16_f32 v17, v18, v19
	global_store_dwordx2 v[56:57], v[16:17], off offset:1040
	v_mfma_f32_32x32x16_bf16 v[0:15], v[48:51], v[116:119], v[0:15]
	v_lshlrev_b32_e32 v62, 16, v158
	v_and_b32_e32 v63, 0xffff0000, v158
	v_lshlrev_b32_e32 v64, 16, v159
	v_and_b32_e32 v65, 0xffff0000, v159
	v_fma_f32 v16, v20, v224, v145
	v_fma_f32 v17, v21, v225, v145
	v_mfma_f32_32x32x16_bf16 v[0:15], v[44:47], v[104:107], v[0:15]
	v_fma_f32 v18, v22, v226, v145
	v_fma_f32 v19, v23, v227, v145
	v_mul_f32_e32 v44, v16, v62
	v_mul_f32_e32 v45, v17, v63
	v_mul_f32_e32 v46, v18, v64
	v_mul_f32_e32 v47, v19, v65
	v_mul_f32_e32 v16, v186, v44
	v_mul_f32_e32 v17, v187, v45
	v_mul_f32_e32 v18, v188, v46
	v_mul_f32_e32 v19, v189, v47
	v_cvt_pk_bf16_f32 v16, v16, v17
	v_cvt_pk_bf16_f32 v17, v18, v19
	global_store_dwordx2 v[56:57], v[16:17], off offset:1056
	v_mfma_f32_32x32x16_bf16 v[0:15], v[40:43], v[92:95], v[0:15]
	v_lshlrev_b32_e32 v40, 16, v156
	v_and_b32_e32 v41, 0xffff0000, v156
	v_lshlrev_b32_e32 v42, 16, v157
	v_and_b32_e32 v43, 0xffff0000, v157
	v_fma_f32 v16, v24, v228, v145
	v_fma_f32 v17, v25, v229, v145
	v_fma_f32 v18, v26, v230, v145
	v_fma_f32 v19, v27, v231, v145
	v_mul_f32_e32 v24, v16, v40
	v_mul_f32_e32 v25, v17, v41
	v_mul_f32_e32 v26, v18, v42
	v_mul_f32_e32 v27, v19, v43
	v_mul_f32_e32 v16, v190, v24
	v_mul_f32_e32 v17, v191, v25
	v_mul_f32_e32 v18, v192, v26
	v_mul_f32_e32 v19, v193, v27
	v_cvt_pk_bf16_f32 v16, v16, v17
	v_cvt_pk_bf16_f32 v17, v18, v19
	global_store_dwordx2 v[56:57], v[16:17], off offset:1072
	v_mfma_f32_32x32x16_bf16 v[0:15], v[36:39], v[80:83], v[0:15]
	v_mul_f32_e32 v25, v25, v25
	v_mul_f32_e32 v27, v27, v27
	v_fmac_f32_e32 v25, v24, v24
	v_fmac_f32_e32 v27, v26, v26
	v_add_f32_e32 v24, v25, v27
	v_mfma_f32_32x32x16_bf16 v[0:15], v[32:35], v[68:71], v[0:15]
	v_lshlrev_b32_e32 v32, 16, v154
	v_and_b32_e32 v33, 0xffff0000, v154
	v_lshlrev_b32_e32 v34, 16, v155
	v_and_b32_e32 v35, 0xffff0000, v155
	v_mfma_f32_32x32x16_bf16 v[0:15], v[28:31], v[58:61], v[0:15]
	s_nop 11
	v_fma_f32 v0, v0, v232, v145
	v_fma_f32 v1, v1, v233, v145
	v_fma_f32 v2, v2, v234, v145
	v_fma_f32 v3, v3, v235, v145
	v_mul_f32_e32 v28, v0, v32
	v_mul_f32_e32 v29, v1, v33
	v_mul_f32_e32 v30, v2, v34
	v_mul_f32_e32 v31, v3, v35
	v_mul_f32_e32 v0, v200, v28
	v_mul_f32_e32 v1, v201, v29
	v_mul_f32_e32 v2, v202, v30
	v_mul_f32_e32 v3, v203, v31
	v_cvt_pk_bf16_f32 v0, v0, v1
	v_cvt_pk_bf16_f32 v1, v2, v3
	global_store_dwordx2 v[56:57], v[0:1], off offset:1088
	v_lshlrev_b32_e32 v20, 16, v152
	v_and_b32_e32 v21, 0xffff0000, v152
	v_lshlrev_b32_e32 v22, 16, v153
	v_and_b32_e32 v23, 0xffff0000, v153
	v_and_b32_e32 v33, 64, v167
	v_xor_b32_e32 v32, 32, v167
	v_add_u32_e32 v33, 64, v33
	v_cmp_lt_i32_e32 vcc, v32, v33
	v_mul_f32_e32 v33, v76, v76
	v_mul_f32_e32 v34, v78, v78
	v_fmac_f32_e32 v33, v67, v67
	v_fmac_f32_e32 v34, v77, v77
	v_add_f32_e32 v33, v33, v34
	v_mul_f32_e32 v34, v53, v53
	v_mul_f32_e32 v35, v55, v55
	v_fmac_f32_e32 v34, v52, v52
	v_fmac_f32_e32 v35, v54, v54
	v_add_f32_e32 v34, v34, v35
	v_add_f32_e32 v33, v33, v34
	v_mul_f32_e32 v34, v45, v45
	v_mul_f32_e32 v35, v47, v47
	v_fmac_f32_e32 v34, v44, v44
	v_fmac_f32_e32 v35, v46, v46
	v_add_f32_e32 v34, v34, v35
	v_mul_f32_e32 v25, v29, v29
	v_mul_f32_e32 v26, v31, v31
	v_add_f32_e32 v33, v33, v34
	v_fmac_f32_e32 v25, v28, v28
	v_fmac_f32_e32 v26, v30, v30
	v_add_f32_e32 v24, v33, v24
	v_add_f32_e32 v25, v25, v26
	v_add_f32_e32 v24, v24, v25
	v_cndmask_b32_e32 v32, v167, v32, vcc
	v_fma_f32 v0, v4, v236, v145
	v_fma_f32 v1, v5, v237, v145
	v_fma_f32 v2, v6, v238, v145
	v_fma_f32 v3, v7, v239, v145
	v_mul_f32_e32 v20, v0, v20
	v_mul_f32_e32 v21, v1, v21
	v_mul_f32_e32 v22, v2, v22
	v_mul_f32_e32 v23, v3, v23
	v_mul_f32_e32 v0, v204, v20
	v_mul_f32_e32 v1, v205, v21
	v_mul_f32_e32 v2, v206, v22
	v_mul_f32_e32 v3, v207, v23
	v_cvt_pk_bf16_f32 v0, v0, v1
	v_cvt_pk_bf16_f32 v1, v2, v3
	global_store_dwordx2 v[56:57], v[0:1], off offset:1104
	v_lshlrev_b32_e32 v16, 16, v150
	v_and_b32_e32 v17, 0xffff0000, v150
	v_lshlrev_b32_e32 v18, 16, v151
	v_and_b32_e32 v19, 0xffff0000, v151
	v_mul_f32_e32 v21, v21, v21
	v_mul_f32_e32 v23, v23, v23
	v_fmac_f32_e32 v21, v20, v20
	v_fmac_f32_e32 v23, v22, v22
	v_add_f32_e32 v20, v21, v23
	v_add_f32_e32 v20, v24, v20
	v_fma_f32 v0, v8, v240, v145
	v_fma_f32 v1, v9, v241, v145
	v_fma_f32 v2, v10, v242, v145
	v_fma_f32 v3, v11, v243, v145
	v_mul_f32_e32 v8, v0, v16
	v_mul_f32_e32 v9, v1, v17
	v_mul_f32_e32 v10, v2, v18
	v_mul_f32_e32 v11, v3, v19
	v_mul_f32_e32 v0, v208, v8
	v_mul_f32_e32 v1, v209, v9
	v_mul_f32_e32 v2, v210, v10
	v_mul_f32_e32 v3, v211, v11
	v_cvt_pk_bf16_f32 v0, v0, v1
	v_cvt_pk_bf16_f32 v1, v2, v3
	global_store_dwordx2 v[56:57], v[0:1], off offset:1120
	v_mul_f32_e32 v9, v9, v9
	v_mul_f32_e32 v11, v11, v11
	v_and_b32_e32 v17, 0xffff0000, v148
	v_and_b32_e32 v19, 0xffff0000, v149
	v_fmac_f32_e32 v9, v8, v8
	v_fmac_f32_e32 v11, v10, v10
	v_lshlrev_b32_e32 v16, 16, v148
	v_lshlrev_b32_e32 v18, 16, v149
	v_add_f32_e32 v8, v9, v11
	v_add_f32_e32 v8, v20, v8
	v_fma_f32 v0, v12, v244, v145
	v_fma_f32 v1, v13, v245, v145
	v_fma_f32 v2, v14, v246, v145
	v_fmac_f32_e32 v145, v15, v247
	v_mul_f32_e32 v1, v1, v17
	v_mul_f32_e32 v9, v145, v19
	v_mul_f32_e32 v0, v0, v16
	v_mul_f32_e32 v3, v2, v18
	v_mul_f32_e32 v10, v1, v1
	v_mul_f32_e32 v11, v9, v9
	v_fmac_f32_e32 v10, v0, v0
	v_fmac_f32_e32 v11, v3, v3
	v_mul_f32_e32 v2, v248, v0
	v_mul_f32_e32 v1, v249, v1
	v_add_f32_e32 v0, v10, v11
	v_cvt_pk_bf16_f32 v2, v2, v1
	v_add_f32_e32 v0, v8, v0
	v_lshlrev_b32_e32 v1, 2, v32
	ds_bpermute_b32 v1, v1, v0
	v_mul_f32_e32 v3, v250, v3
	v_mul_f32_e32 v4, v251, v9
	v_cvt_pk_bf16_f32 v3, v3, v4
	global_store_dwordx2 v[56:57], v[2:3], off offset:1136
	s_and_saveexec_b64 s[12:13], s[0:1]
	s_cbranch_execz .LBB0_966
	v_lshlrev_b64 v[2:3], 5, v[146:147]
	v_lshl_add_u64 v[2:3], s[6:7], 0, v[2:3]
	s_lshl_b32 s10, s21, 3
	v_lshl_add_u64 v[2:3], v[2:3], 0, s[10:11]
	v_mov_b32_e32 v145, v133
	v_lshl_add_u64 v[2:3], v[2:3], 0, v[144:145]
	s_waitcnt lgkmcnt(0)
	v_add_f32_e32 v0, v0, v1
	global_store_dword v[2:3], v0, off
	s_branch .LBB0_966
